# nt (non-temporal) hint on the 16 x-row loads of phase B (x is streamed once; keep it out of the caches)
# speedup vs baseline: 1.0138x; 1.0138x over previous
.LBB0_178:
	v_add_co_u32_e64 v76, s[0:1], s22, v62
	v_add_u32_e32 v10, 0xffffdfff, v60
	s_nop 0
	v_addc_co_u32_e64 v77, s[0:1], -1, v63, s[0:1]
	v_lshl_add_u64 v[2:3], v[60:61], 0, -1
	v_cmp_gt_i32_e64 s[0:1], s17, v54
	v_add_u32_e32 v4, 0xffffe000, v60
	v_cmp_gt_i32_e32 vcc, s17, v60
	v_lshl_add_u64 v[6:7], v[60:61], 0, 1
	v_lshl_add_u64 v[8:9], v[60:61], 0, 2
	v_cndmask_b32_e64 v3, 0, v3, s[0:1]
	v_cndmask_b32_e64 v2, v10, v2, s[0:1]
	v_cndmask_b32_e32 v5, 0, v61, vcc
	v_add_u32_e32 v11, 0xffffe001, v60
	v_add_u32_e32 v12, 0xffffe002, v60
	v_cndmask_b32_e64 v15, v55, v92, s[0:1]
	v_cndmask_b32_e64 v14, v93, v94, s[0:1]
	v_cndmask_b32_e32 v4, v4, v60, vcc
	v_cndmask_b32_e32 v17, v55, v92, vcc
	v_cndmask_b32_e32 v16, v93, v94, vcc
	v_cmp_gt_i32_e32 vcc, s17, v6
	v_cmp_gt_i32_e64 s[2:3], s17, v8
	v_lshlrev_b64 v[2:3], 12, v[2:3]
	v_cndmask_b32_e32 v7, 0, v7, vcc
	v_cndmask_b32_e64 v9, 0, v9, s[2:3]
	v_lshrrev_b32_e32 v18, 12, v10
	v_lshlrev_b64 v[4:5], 12, v[4:5]
	v_cndmask_b32_e32 v6, v11, v6, vcc
	v_cndmask_b32_e64 v8, v12, v8, s[2:3]
	v_lshl_add_u64 v[2:3], v[14:15], 0, v[2:3]
	v_cndmask_b32_e32 v11, v55, v92, vcc
	v_cndmask_b32_e32 v10, v93, v94, vcc
	v_cndmask_b32_e64 v13, v55, v92, s[2:3]
	v_cndmask_b32_e64 v12, v93, v94, s[2:3]
	v_mad_u32_u24 v18, v18, s21, s21
	v_lshl_add_u64 v[4:5], v[16:17], 0, v[4:5]
	v_lshlrev_b64 v[6:7], 12, v[6:7]
	v_lshlrev_b64 v[8:9], 12, v[8:9]
	v_lshl_add_u64 v[2:3], v[2:3], 0, v[64:65]
	global_load_dwordx4 v[26:29], v[58:59], off
	v_cndmask_b32_e64 v56, v18, 0, s[0:1]
	v_lshl_add_u64 v[14:15], v[4:5], 0, v[64:65]
	v_lshl_add_u64 v[10:11], v[10:11], 0, v[6:7]
	v_lshl_add_u64 v[12:13], v[12:13], 0, v[8:9]
	global_load_dwordx4 v[96:99], v[2:3], off nt
	global_load_dwordx4 v[38:41], v[2:3], off offset:1024 nt
	global_load_dwordx4 v[100:103], v[14:15], off nt
	global_load_dwordx4 v[42:45], v[14:15], off offset:1024 nt
	global_load_dwordx4 v[18:21], v[2:3], off offset:2048 nt
	s_nop 0
	global_load_dwordx4 v[2:5], v[2:3], off offset:3072 nt
	s_nop 0
	global_load_dwordx4 v[22:25], v[14:15], off offset:2048 nt
	global_load_dwordx4 v[6:9], v[14:15], off offset:3072 nt
	v_lshl_add_u64 v[16:17], v[56:57], 2, s[28:29]
	v_lshl_add_u64 v[10:11], v[10:11], 0, v[64:65]
	v_lshl_add_u64 v[14:15], v[12:13], 0, v[64:65]
	v_lshl_add_u64 v[80:81], v[16:17], 0, s[18:19]
	v_lshl_add_u64 v[78:79], v[16:17], 0, v[68:69]
	global_load_dwordx4 v[104:107], v[10:11], off nt
	global_load_dwordx4 v[46:49], v[10:11], off offset:1024 nt
	global_load_dwordx4 v[108:111], v[14:15], off nt
	global_load_dwordx4 v[50:53], v[14:15], off offset:1024 nt
	global_load_dwordx4 v[30:33], v[10:11], off offset:2048 nt
	s_nop 0
	global_load_dwordx4 v[10:13], v[10:11], off offset:3072 nt
	s_nop 0
	global_load_dwordx4 v[34:37], v[14:15], off offset:2048 nt
	s_nop 0
	global_load_dwordx4 v[14:17], v[14:15], off offset:3072 nt
	v_lshl_add_u64 v[112:113], v[80:81], 0, v[68:69]
	global_load_dwordx4 v[112:115], v[112:113], off
	s_nop 0
	global_load_dwordx4 v[116:119], v[78:79], off
	v_lshl_add_u64 v[120:121], v[80:81], 0, v[70:71]
	v_lshl_add_u64 v[88:89], v[80:81], 0, v[72:73]
	v_add_u32_e32 v54, s10, v54
	v_lshl_add_u64 v[60:61], v[60:61], 0, s[10:11]
	s_waitcnt vmcnt(17)
	v_pk_mul_f32 v[122:123], v[98:99], v[98:99]
	v_pk_mul_f32 v[124:125], v[96:97], v[96:97]
	s_waitcnt vmcnt(16)
	v_pk_mul_f32 v[126:127], v[40:41], v[40:41]
	v_pk_mul_f32 v[128:129], v[38:39], v[38:39]
	s_waitcnt vmcnt(15)
	v_pk_mul_f32 v[130:131], v[102:103], v[102:103]
	v_pk_mul_f32 v[132:133], v[100:101], v[100:101]
	s_waitcnt vmcnt(14)
	v_pk_mul_f32 v[134:135], v[44:45], v[44:45]
	v_pk_mul_f32 v[136:137], v[42:43], v[42:43]
	v_pk_mov_b32 v[138:139], v[124:125], v[122:123] op_sel:[1,0]
	v_mov_b32_e32 v125, v123
	v_pk_mov_b32 v[122:123], v[128:129], v[126:127] op_sel:[1,0]
	v_mov_b32_e32 v129, v127
	v_pk_mov_b32 v[126:127], v[132:133], v[130:131] op_sel:[1,0]
	v_mov_b32_e32 v133, v131
	v_pk_mov_b32 v[130:131], v[136:137], v[134:135] op_sel:[1,0]
	v_mov_b32_e32 v137, v135
	s_waitcnt vmcnt(13)
	v_mul_f32_e32 v56, v19, v19
	v_mul_f32_e32 v82, v21, v21
	s_waitcnt vmcnt(11)
	v_mul_f32_e32 v84, v23, v23
	v_mul_f32_e32 v86, v25, v25
	s_waitcnt vmcnt(9)
	v_pk_mul_f32 v[134:135], v[106:107], v[106:107]
	v_pk_mul_f32 v[140:141], v[104:105], v[104:105]
	s_waitcnt vmcnt(8)
	v_pk_mul_f32 v[142:143], v[48:49], v[48:49]
	v_pk_mul_f32 v[144:145], v[46:47], v[46:47]
	s_waitcnt vmcnt(7)
	v_pk_mul_f32 v[146:147], v[110:111], v[110:111]
	v_pk_mul_f32 v[148:149], v[108:109], v[108:109]
	s_waitcnt vmcnt(6)
	v_pk_mul_f32 v[150:151], v[52:53], v[52:53]
	v_pk_mul_f32 v[152:153], v[50:51], v[50:51]
	v_pk_add_f32 v[124:125], v[138:139], v[124:125]
	v_pk_add_f32 v[122:123], v[122:123], v[128:129]
	v_pk_add_f32 v[126:127], v[126:127], v[132:133]
	v_pk_add_f32 v[128:129], v[130:131], v[136:137]
	v_mul_f32_e32 v95, v4, v4
	v_mul_f32_e32 v162, v5, v5
	v_mul_f32_e32 v163, v8, v8
	v_mul_f32_e32 v164, v9, v9
	v_mul_f32_e32 v165, v2, v2
	v_mul_f32_e32 v166, v3, v3
	v_mul_f32_e32 v167, v6, v6
	v_mul_f32_e32 v168, v7, v7
	v_pk_fma_f32 v[154:155], v[18:19], v[18:19], v[56:57] op_sel_hi:[1,1,0]
	v_pk_fma_f32 v[156:157], v[20:21], v[20:21], v[82:83] op_sel_hi:[1,1,0]
	v_pk_fma_f32 v[158:159], v[22:23], v[22:23], v[84:85] op_sel_hi:[1,1,0]
	v_pk_fma_f32 v[160:161], v[24:25], v[24:25], v[86:87] op_sel_hi:[1,1,0]
	v_pk_mov_b32 v[130:131], v[140:141], v[134:135] op_sel:[1,0]
	v_mov_b32_e32 v141, v135
	v_pk_mov_b32 v[132:133], v[144:145], v[142:143] op_sel:[1,0]
	v_mov_b32_e32 v145, v143
	v_pk_mov_b32 v[134:135], v[148:149], v[146:147] op_sel:[1,0]
	v_mov_b32_e32 v149, v147
	v_pk_mov_b32 v[136:137], v[152:153], v[150:151] op_sel:[1,0]
	v_mov_b32_e32 v153, v151
	v_pk_add_f32 v[124:125], v[124:125], v[124:125] op_sel:[0,1] op_sel_hi:[1,0]
	v_pk_add_f32 v[122:123], v[122:123], v[122:123] op_sel:[0,1] op_sel_hi:[1,0]
	v_pk_add_f32 v[126:127], v[126:127], v[126:127] op_sel:[0,1] op_sel_hi:[1,0]
	v_pk_add_f32 v[128:129], v[128:129], v[128:129] op_sel:[0,1] op_sel_hi:[1,0]
	s_waitcnt vmcnt(5)
	v_mul_f32_e32 v56, v31, v31
	v_mul_f32_e32 v82, v33, v33
	s_waitcnt vmcnt(3)
	v_mul_f32_e32 v84, v35, v35
	v_mul_f32_e32 v86, v37, v37
	v_mov_b32_e32 v155, v95
	v_mov_b32_e32 v157, v162
	v_mov_b32_e32 v159, v163
	v_mov_b32_e32 v161, v164
	v_pk_add_f32 v[130:131], v[130:131], v[140:141]
	v_pk_add_f32 v[132:133], v[132:133], v[144:145]
	v_pk_add_f32 v[134:135], v[134:135], v[148:149]
	v_pk_add_f32 v[136:137], v[136:137], v[152:153]
	v_mov_b32_e32 v125, v165
	v_mov_b32_e32 v123, v166
	v_mov_b32_e32 v127, v167
	v_mov_b32_e32 v129, v168
	v_mul_f32_e32 v169, v12, v12
	v_mul_f32_e32 v170, v13, v13
	s_waitcnt vmcnt(2)
	v_mul_f32_e32 v171, v16, v16
	v_mul_f32_e32 v172, v17, v17
	v_mul_f32_e32 v173, v10, v10
	v_mul_f32_e32 v174, v11, v11
	v_mul_f32_e32 v175, v14, v14
	v_mul_f32_e32 v176, v15, v15
	v_pk_fma_f32 v[138:139], v[30:31], v[30:31], v[56:57] op_sel_hi:[1,1,0]
	v_pk_fma_f32 v[142:143], v[32:33], v[32:33], v[82:83] op_sel_hi:[1,1,0]
	v_pk_fma_f32 v[146:147], v[34:35], v[34:35], v[84:85] op_sel_hi:[1,1,0]
	v_pk_fma_f32 v[150:151], v[36:37], v[36:37], v[86:87] op_sel_hi:[1,1,0]
	v_pk_add_f32 v[154:155], v[154:155], v[156:157]
	v_pk_add_f32 v[156:157], v[158:159], v[160:161]
	v_pk_add_f32 v[130:131], v[130:131], v[130:131] op_sel:[0,1] op_sel_hi:[1,0]
	v_pk_add_f32 v[132:133], v[132:133], v[132:133] op_sel:[0,1] op_sel_hi:[1,0]
	v_pk_add_f32 v[134:135], v[134:135], v[134:135] op_sel:[0,1] op_sel_hi:[1,0]
	v_pk_add_f32 v[136:137], v[136:137], v[136:137] op_sel:[0,1] op_sel_hi:[1,0]
	v_pk_add_f32 v[122:123], v[124:125], v[122:123]
	v_pk_add_f32 v[124:125], v[126:127], v[128:129]
	v_mov_b32_e32 v139, v169
	v_mov_b32_e32 v143, v170
	v_mov_b32_e32 v147, v171
	v_mov_b32_e32 v151, v172
	v_mov_b32_e32 v131, v173
	v_mov_b32_e32 v133, v174
	v_mov_b32_e32 v135, v175
	v_mov_b32_e32 v137, v176
	v_pk_add_f32 v[122:123], v[122:123], v[154:155]
	v_pk_add_f32 v[124:125], v[124:125], v[156:157]
	v_pk_add_f32 v[138:139], v[138:139], v[142:143]
	v_pk_add_f32 v[140:141], v[146:147], v[150:151]
	v_pk_add_f32 v[126:127], v[130:131], v[132:133]
	v_pk_add_f32 v[128:129], v[134:135], v[136:137]
	v_mov_b32_e32 v130, v124
	v_mov_b32_e32 v131, v122
	v_mov_b32_e32 v122, v125
	v_pk_add_f32 v[124:125], v[126:127], v[138:139]
	v_pk_add_f32 v[126:127], v[128:129], v[140:141]
	v_pk_add_f32 v[122:123], v[130:131], v[122:123]
	v_mov_b32_e32 v128, v126
	v_mov_b32_e32 v129, v124
	v_mov_b32_e32 v124, v127
	ds_bpermute_b32 v127, v1, v123
	ds_bpermute_b32 v126, v1, v122
	v_pk_add_f32 v[124:125], v[128:129], v[124:125]
	ds_bpermute_b32 v129, v1, v125
	ds_bpermute_b32 v128, v1, v124
	s_waitcnt vmcnt(1)
	v_pk_add_f32 v[112:113], v[112:113], 1.0 op_sel_hi:[1,0]
	s_waitcnt lgkmcnt(2)
	v_pk_add_f32 v[122:123], v[122:123], v[126:127]
	ds_bpermute_b32 v127, v83, v123
	ds_bpermute_b32 v126, v83, v122
	s_waitcnt lgkmcnt(2)
	v_pk_add_f32 v[124:125], v[124:125], v[128:129]
	ds_bpermute_b32 v129, v83, v125
	ds_bpermute_b32 v128, v83, v124
	v_pk_add_f32 v[114:115], v[114:115], 1.0 op_sel_hi:[1,0]
	s_waitcnt lgkmcnt(2)
	v_pk_add_f32 v[122:123], v[122:123], v[126:127]
	ds_bpermute_b32 v127, v85, v123
	ds_bpermute_b32 v126, v85, v122
	s_waitcnt lgkmcnt(2)
	v_pk_add_f32 v[124:125], v[124:125], v[128:129]
	ds_bpermute_b32 v129, v85, v125
	ds_bpermute_b32 v128, v85, v124
	s_waitcnt lgkmcnt(2)
	v_pk_add_f32 v[122:123], v[122:123], v[126:127]
	ds_bpermute_b32 v127, v87, v123
	ds_bpermute_b32 v126, v87, v122
	s_waitcnt lgkmcnt(2)
	v_pk_add_f32 v[124:125], v[124:125], v[128:129]
	ds_bpermute_b32 v129, v87, v125
	ds_bpermute_b32 v128, v87, v124
	s_waitcnt lgkmcnt(2)
	v_pk_add_f32 v[122:123], v[122:123], v[126:127]
	ds_bpermute_b32 v127, v90, v123
	ds_bpermute_b32 v126, v90, v122
	s_waitcnt lgkmcnt(2)
	v_pk_add_f32 v[124:125], v[124:125], v[128:129]
	ds_bpermute_b32 v129, v90, v125
	ds_bpermute_b32 v128, v90, v124
	s_waitcnt lgkmcnt(2)
	v_pk_add_f32 v[122:123], v[122:123], v[126:127]
	ds_bpermute_b32 v127, v91, v123
	ds_bpermute_b32 v126, v91, v122
	s_waitcnt lgkmcnt(2)
	v_pk_add_f32 v[124:125], v[124:125], v[128:129]
	ds_bpermute_b32 v129, v91, v125
	ds_bpermute_b32 v128, v91, v124
	s_waitcnt lgkmcnt(2)
	v_pk_add_f32 v[122:123], v[122:123], v[126:127]
	s_nop 0
	v_pk_fma_f32 v[122:123], v[122:123], s[16:17], v[66:67] op_sel_hi:[1,0,0]
	s_waitcnt lgkmcnt(0)
	v_pk_add_f32 v[124:125], v[124:125], v[128:129]
	v_mul_f32_e32 v82, 0x4b800000, v123
	v_cmp_gt_f32_e64 s[0:1], s20, v123
	v_mul_f32_e32 v56, 0x4b800000, v122
	v_cmp_gt_f32_e32 vcc, s20, v122
	v_pk_fma_f32 v[124:125], v[124:125], s[16:17], v[66:67] op_sel_hi:[1,0,0]
	v_cndmask_b32_e64 v82, v123, v82, s[0:1]
	v_cndmask_b32_e32 v56, v122, v56, vcc
	v_mul_f32_e32 v84, 0x4b800000, v124
	v_cmp_gt_f32_e64 s[2:3], s20, v124
	v_mul_f32_e32 v86, 0x4b800000, v125
	v_cmp_gt_f32_e64 s[4:5], s20, v125
	v_rsq_f32_e32 v82, v82
	v_cndmask_b32_e64 v84, v124, v84, s[2:3]
	v_cndmask_b32_e64 v86, v125, v86, s[4:5]
	v_rsq_f32_e32 v56, v56
	v_rsq_f32_e32 v86, v86
	v_rsq_f32_e32 v84, v84
	v_mul_f32_e32 v95, 0x45800000, v82
	v_mul_f32_e32 v122, 0x45800000, v56
	v_cndmask_b32_e64 v82, v82, v95, s[0:1]
	v_cndmask_b32_e32 v56, v56, v122, vcc
	v_mul_f32_e32 v95, 0x45800000, v86
	v_mul_f32_e32 v122, 0x45800000, v84
	v_pk_mul_f32 v[96:97], v[96:97], v[82:83] op_sel_hi:[1,0]
	v_pk_mul_f32 v[98:99], v[98:99], v[82:83] op_sel_hi:[1,0]
	v_cndmask_b32_e64 v86, v86, v95, s[4:5]
	v_cndmask_b32_e64 v84, v84, v122, s[2:3]
	v_pk_mul_f32 v[96:97], v[96:97], v[26:27]
	v_pk_mul_f32 v[102:103], v[102:103], v[56:57] op_sel_hi:[1,0]
	v_pk_mul_f32 v[100:101], v[100:101], v[56:57] op_sel_hi:[1,0]
	v_pk_mul_f32 v[104:105], v[104:105], v[86:87] op_sel_hi:[1,0]
	v_pk_mul_f32 v[108:109], v[108:109], v[84:85] op_sel_hi:[1,0]
	v_pk_mul_f32 v[98:99], v[98:99], v[28:29]
	s_waitcnt vmcnt(0)
	v_pk_fma_f32 v[96:97], v[96:97], v[112:113], v[116:117]
	v_pk_mul_f32 v[106:107], v[106:107], v[86:87] op_sel_hi:[1,0]
	v_pk_mul_f32 v[110:111], v[110:111], v[84:85] op_sel_hi:[1,0]
	v_pk_mul_f32 v[100:101], v[100:101], v[26:27]
	v_pk_mul_f32 v[102:103], v[102:103], v[28:29]
	v_pk_mul_f32 v[104:105], v[26:27], v[104:105]
	v_pk_mul_f32 v[26:27], v[26:27], v[108:109]
	v_pk_fma_f32 v[98:99], v[98:99], v[114:115], v[118:119]
	v_cvt_pk_bf16_f32 v96, v96, v97
	v_pk_mul_f32 v[106:107], v[28:29], v[106:107]
	v_cvt_pk_bf16_f32 v97, v98, v99
	v_pk_mul_f32 v[28:29], v[28:29], v[110:111]
	v_pk_fma_f32 v[102:103], v[102:103], v[114:115], v[118:119]
	v_pk_fma_f32 v[100:101], v[100:101], v[112:113], v[116:117]
	v_pk_fma_f32 v[26:27], v[112:113], v[26:27], v[116:117]
	global_store_dwordx2 v[76:77], v[96:97], off offset:-3584
	v_cvt_pk_bf16_f32 v96, v100, v101
	v_cvt_pk_bf16_f32 v97, v102, v103
	v_pk_fma_f32 v[106:107], v[114:115], v[106:107], v[118:119]
	v_pk_fma_f32 v[28:29], v[114:115], v[28:29], v[118:119]
	v_pk_fma_f32 v[104:105], v[112:113], v[104:105], v[116:117]
	global_store_dwordx2 v[76:77], v[96:97], off offset:-1536
	v_cvt_pk_bf16_f32 v96, v104, v105
	v_cvt_pk_bf16_f32 v97, v106, v107
	global_store_dwordx2 v[62:63], v[96:97], off offset:-3584
	v_cvt_pk_bf16_f32 v26, v26, v27
	v_cvt_pk_bf16_f32 v27, v28, v29
	global_store_dwordx2 v[62:63], v[26:27], off offset:-1536
	global_load_dwordx4 v[26:29], v[58:59], off offset:1024
	s_nop 0
	global_load_dwordx4 v[96:99], v[120:121], off
	global_load_dwordx4 v[100:103], v[78:79], off offset:1024
	v_pk_mul_f32 v[40:41], v[40:41], v[82:83] op_sel_hi:[1,0]
	v_pk_mul_f32 v[38:39], v[38:39], v[82:83] op_sel_hi:[1,0]
	v_pk_mul_f32 v[44:45], v[44:45], v[56:57] op_sel_hi:[1,0]
	v_pk_mul_f32 v[48:49], v[48:49], v[86:87] op_sel_hi:[1,0]
	v_pk_mul_f32 v[52:53], v[52:53], v[84:85] op_sel_hi:[1,0]
	v_pk_mul_f32 v[42:43], v[42:43], v[56:57] op_sel_hi:[1,0]
	v_pk_mul_f32 v[46:47], v[46:47], v[86:87] op_sel_hi:[1,0]
	v_pk_mul_f32 v[50:51], v[50:51], v[84:85] op_sel_hi:[1,0]
	v_pk_mul_f32 v[18:19], v[18:19], v[82:83] op_sel_hi:[1,0]
	v_pk_mul_f32 v[20:21], v[20:21], v[82:83] op_sel_hi:[1,0]
	v_pk_mul_f32 v[24:25], v[24:25], v[56:57] op_sel_hi:[1,0]
	v_pk_mul_f32 v[22:23], v[22:23], v[56:57] op_sel_hi:[1,0]
	v_pk_mul_f32 v[32:33], v[32:33], v[86:87] op_sel_hi:[1,0]
	v_pk_mul_f32 v[30:31], v[30:31], v[86:87] op_sel_hi:[1,0]
	v_pk_mul_f32 v[36:37], v[36:37], v[84:85] op_sel_hi:[1,0]
	v_pk_mul_f32 v[34:35], v[34:35], v[84:85] op_sel_hi:[1,0]
	v_pk_mul_f32 v[2:3], v[2:3], v[82:83] op_sel_hi:[1,0]
	v_pk_mul_f32 v[4:5], v[4:5], v[82:83] op_sel_hi:[1,0]
	v_pk_mul_f32 v[8:9], v[8:9], v[56:57] op_sel_hi:[1,0]
	v_pk_mul_f32 v[6:7], v[6:7], v[56:57] op_sel_hi:[1,0]
	v_pk_mul_f32 v[12:13], v[12:13], v[86:87] op_sel_hi:[1,0]
	v_pk_mul_f32 v[10:11], v[10:11], v[86:87] op_sel_hi:[1,0]
	v_pk_mul_f32 v[16:17], v[16:17], v[84:85] op_sel_hi:[1,0]
	v_pk_mul_f32 v[14:15], v[14:15], v[84:85] op_sel_hi:[1,0]
	v_cmp_lt_i32_e32 vcc, s23, v54
	s_or_b64 s[14:15], vcc, s[14:15]
	s_waitcnt vmcnt(2)
	v_pk_mul_f32 v[38:39], v[38:39], v[26:27]
	v_pk_mul_f32 v[40:41], v[40:41], v[28:29]
	v_pk_mul_f32 v[44:45], v[44:45], v[28:29]
	v_pk_mul_f32 v[48:49], v[48:49], v[28:29]
	v_pk_mul_f32 v[28:29], v[52:53], v[28:29]
	s_waitcnt vmcnt(1)
	v_pk_add_f32 v[52:53], v[96:97], 1.0 op_sel_hi:[1,0]
	v_pk_mul_f32 v[42:43], v[42:43], v[26:27]
	v_pk_mul_f32 v[46:47], v[46:47], v[26:27]
	v_pk_mul_f32 v[26:27], v[50:51], v[26:27]
	v_pk_add_f32 v[50:51], v[98:99], 1.0 op_sel_hi:[1,0]
	s_waitcnt vmcnt(0)
	v_pk_fma_f32 v[38:39], v[38:39], v[52:53], v[100:101]
	v_pk_fma_f32 v[40:41], v[40:41], v[50:51], v[102:103]
	v_cvt_pk_bf16_f32 v38, v38, v39
	v_pk_fma_f32 v[44:45], v[44:45], v[50:51], v[102:103]
	v_cvt_pk_bf16_f32 v39, v40, v41
	v_pk_fma_f32 v[42:43], v[42:43], v[52:53], v[100:101]
	v_pk_fma_f32 v[26:27], v[26:27], v[52:53], v[100:101]
	global_store_dwordx2 v[76:77], v[38:39], off offset:-3072
	v_cvt_pk_bf16_f32 v38, v42, v43
	v_cvt_pk_bf16_f32 v39, v44, v45
	v_pk_fma_f32 v[48:49], v[48:49], v[50:51], v[102:103]
	v_pk_fma_f32 v[28:29], v[28:29], v[50:51], v[102:103]
	v_pk_fma_f32 v[46:47], v[46:47], v[52:53], v[100:101]
	global_store_dwordx2 v[76:77], v[38:39], off offset:-1024
	v_cvt_pk_bf16_f32 v38, v46, v47
	v_cvt_pk_bf16_f32 v39, v48, v49
	global_store_dwordx2 v[62:63], v[38:39], off offset:-3072
	v_cvt_pk_bf16_f32 v26, v26, v27
	v_cvt_pk_bf16_f32 v27, v28, v29
	global_store_dwordx2 v[62:63], v[26:27], off offset:-1024
	global_load_dwordx4 v[26:29], v[88:89], off
	s_nop 0
	global_load_dwordx4 v[38:41], v[58:59], off offset:2048
	global_load_dwordx4 v[42:45], v[78:79], off offset:2048
	v_lshl_add_u64 v[46:47], v[80:81], 0, v[74:75]
	s_waitcnt vmcnt(2)
	v_pk_add_f32 v[26:27], v[26:27], 1.0 op_sel_hi:[1,0]
	s_waitcnt vmcnt(1)
	v_pk_mul_f32 v[18:19], v[18:19], v[38:39]
	v_pk_add_f32 v[28:29], v[28:29], 1.0 op_sel_hi:[1,0]
	v_pk_mul_f32 v[20:21], v[20:21], v[40:41]
	s_waitcnt vmcnt(0)
	v_pk_fma_f32 v[18:19], v[18:19], v[26:27], v[42:43]
	v_pk_mul_f32 v[22:23], v[22:23], v[38:39]
	v_pk_mul_f32 v[24:25], v[24:25], v[40:41]
	v_pk_fma_f32 v[20:21], v[20:21], v[28:29], v[44:45]
	v_cvt_pk_bf16_f32 v18, v18, v19
	v_pk_mul_f32 v[30:31], v[30:31], v[38:39]
	v_cvt_pk_bf16_f32 v19, v20, v21
	v_pk_mul_f32 v[32:33], v[32:33], v[40:41]
	v_pk_fma_f32 v[24:25], v[24:25], v[28:29], v[44:45]
	v_pk_fma_f32 v[22:23], v[22:23], v[26:27], v[42:43]
	global_store_dwordx2 v[76:77], v[18:19], off offset:-2560
	v_cvt_pk_bf16_f32 v18, v22, v23
	v_cvt_pk_bf16_f32 v19, v24, v25
	v_pk_mul_f32 v[34:35], v[34:35], v[38:39]
	v_pk_mul_f32 v[36:37], v[36:37], v[40:41]
	v_pk_fma_f32 v[32:33], v[32:33], v[28:29], v[44:45]
	v_pk_fma_f32 v[30:31], v[30:31], v[26:27], v[42:43]
	global_store_dwordx2 v[76:77], v[18:19], off offset:-512
	v_cvt_pk_bf16_f32 v18, v30, v31
	v_cvt_pk_bf16_f32 v19, v32, v33
	v_pk_fma_f32 v[28:29], v[36:37], v[28:29], v[44:45]
	v_pk_fma_f32 v[26:27], v[34:35], v[26:27], v[42:43]
	global_store_dwordx2 v[62:63], v[18:19], off offset:-2560
	v_cvt_pk_bf16_f32 v18, v26, v27
	v_cvt_pk_bf16_f32 v19, v28, v29
	global_store_dwordx2 v[62:63], v[18:19], off offset:-512
	global_load_dwordx4 v[18:21], v[46:47], off
	s_nop 0
	global_load_dwordx4 v[22:25], v[58:59], off offset:3072
	global_load_dwordx4 v[26:29], v[78:79], off offset:3072
	s_waitcnt vmcnt(2)
	v_pk_add_f32 v[18:19], v[18:19], 1.0 op_sel_hi:[1,0]
	s_waitcnt vmcnt(1)
	v_pk_mul_f32 v[2:3], v[2:3], v[22:23]
	v_pk_add_f32 v[20:21], v[20:21], 1.0 op_sel_hi:[1,0]
	v_pk_mul_f32 v[4:5], v[4:5], v[24:25]
	s_waitcnt vmcnt(0)
	v_pk_fma_f32 v[2:3], v[2:3], v[18:19], v[26:27]
	v_pk_mul_f32 v[6:7], v[6:7], v[22:23]
	v_pk_mul_f32 v[8:9], v[8:9], v[24:25]
	v_pk_fma_f32 v[4:5], v[4:5], v[20:21], v[28:29]
	v_cvt_pk_bf16_f32 v2, v2, v3
	v_pk_mul_f32 v[10:11], v[10:11], v[22:23]
	v_cvt_pk_bf16_f32 v3, v4, v5
	v_pk_mul_f32 v[12:13], v[12:13], v[24:25]
	v_pk_fma_f32 v[8:9], v[8:9], v[20:21], v[28:29]
	v_pk_fma_f32 v[6:7], v[6:7], v[18:19], v[26:27]
	global_store_dwordx2 v[76:77], v[2:3], off offset:-2048
	v_cvt_pk_bf16_f32 v2, v6, v7
	v_cvt_pk_bf16_f32 v3, v8, v9
	v_pk_mul_f32 v[14:15], v[14:15], v[22:23]
	v_pk_mul_f32 v[16:17], v[16:17], v[24:25]
	v_pk_fma_f32 v[12:13], v[12:13], v[20:21], v[28:29]
	v_pk_fma_f32 v[10:11], v[10:11], v[18:19], v[26:27]
	global_store_dwordx2 v[62:63], v[2:3], off offset:-4096
	v_cvt_pk_bf16_f32 v2, v10, v11
	v_cvt_pk_bf16_f32 v3, v12, v13
	v_pk_fma_f32 v[16:17], v[16:17], v[20:21], v[28:29]
	v_pk_fma_f32 v[14:15], v[14:15], v[18:19], v[26:27]
	global_store_dwordx2 v[62:63], v[2:3], off offset:-2048
	v_cvt_pk_bf16_f32 v2, v14, v15
	v_cvt_pk_bf16_f32 v3, v16, v17
	global_store_dwordx2 v[62:63], v[2:3], off
	v_lshl_add_u64 v[62:63], v[62:63], 0, s[12:13]
	s_andn2_b64 exec, exec, s[14:15]
	s_cbranch_execnz .LBB0_178
